# diff attention loop: packed-add trees for the row sums, QK MFMA takes the -max broadcast as C directly (no accumulator copies), shorter max chains
# speedup vs baseline: 1.0382x; 1.0171x over previous
.LBB0_580:
	v_pk_add_f32 v[130:131], v[130:131], v[132:133]
	v_pk_add_f32 v[134:135], v[134:135], v[136:137]
	v_pk_add_f32 v[138:139], v[138:139], v[140:141]
	v_add_f32_e32 v129, v129, v160
	v_exp_f32_e32 v96, v96
	v_exp_f32_e32 v97, v97
	v_exp_f32_e32 v98, v98
	v_exp_f32_e32 v99, v99
	v_pk_add_f32 v[130:131], v[130:131], v[134:135]
	v_pk_add_f32 v[138:139], v[138:139], v[142:143]
	v_exp_f32_e32 v100, v100
	v_exp_f32_e32 v101, v101
	v_exp_f32_e32 v102, v102
	v_exp_f32_e32 v103, v103
	v_pk_add_f32 v[130:131], v[130:131], v[138:139]
	v_pk_add_f32 v[132:133], v[96:97], v[98:99]
	v_add_f32_e32 v129, v129, v130
	v_pk_add_f32 v[134:135], v[100:101], v[102:103]
	v_add_f32_e32 v129, v129, v131
	v_cvt_pk_bf16_f32 v96, v96, v97
	v_cvt_pk_bf16_f32 v97, v98, v99
	v_cvt_pk_bf16_f32 v98, v100, v101
	v_cvt_pk_bf16_f32 v99, v102, v103
	v_add_f32_e32 v220, v220, v129
	v_exp_f32_e32 v104, v104
	v_mfma_f32_32x32x16_bf16 v[48:63], v[112:115], v[96:99], v[48:63]
	v_exp_f32_e32 v105, v105
	v_exp_f32_e32 v106, v106
	v_exp_f32_e32 v107, v107
	v_exp_f32_e32 v108, v108
	v_exp_f32_e32 v109, v109
	v_exp_f32_e32 v110, v110
	v_exp_f32_e32 v111, v111
	v_mfma_f32_32x32x16_bf16 v[16:31], v[116:119], v[96:99], v[16:31]
	v_pk_add_f32 v[132:133], v[132:133], v[134:135]
	v_pk_add_f32 v[136:137], v[104:105], v[106:107]
	v_pk_add_f32 v[138:139], v[108:109], v[110:111]
	v_cvt_pk_bf16_f32 v100, v104, v105
	v_cvt_pk_bf16_f32 v101, v106, v107
	v_cvt_pk_bf16_f32 v102, v108, v109
	v_cvt_pk_bf16_f32 v103, v110, v111
	v_pk_add_f32 v[136:137], v[136:137], v[138:139]
	v_pk_add_f32 v[132:133], v[132:133], v[136:137]
	v_mfma_f32_32x32x16_bf16 v[48:63], v[120:123], v[100:103], v[48:63]
	v_add_f32_e32 v129, v132, v133
	s_add_i32 s23, s23, 1
	s_addk_i32 s22, 0x2000
	v_mfma_f32_32x32x16_bf16 v[16:31], v[124:127], v[100:103], v[16:31]
	s_addk_i32 s21, 0x80
	v_add_f32_e32 v219, v128, v129
	s_cmpk_eq_u32 s22, 0x8000
	s_cbranch_scc1 .LBB0_599
.LBB0_581:
	v_add_u32_e32 v161, s22, v218
	ds_read_b128 v[112:115], v161
	v_add_u32_e32 v160, s22, v217
	v_add_u32_e32 v222, s22, v216
	v_add_u32_e32 v221, s22, v215
	s_or_b32 s0, s23, s18
	s_cmp_eq_u32 s0, 0
	s_cselect_b64 s[14:15], -1, 0
	s_cmp_lg_u32 s0, 0
	s_cselect_b64 s[0:1], -1, 0
	s_waitcnt lgkmcnt(0)
	v_mfma_f32_32x32x16_bf16 v[96:111], v[112:115], v[152:155], v[64:79]
	ds_read_b128 v[112:115], v160
	s_and_b64 vcc, exec, s[14:15]
	s_mov_b64 s[2:3], s[14:15]
	s_waitcnt lgkmcnt(0)
	v_mfma_f32_32x32x16_bf16 v[96:111], v[112:115], v[144:147], v[96:111]
	ds_read_b128 v[112:115], v222
	s_waitcnt lgkmcnt(0)
	v_mfma_f32_32x32x16_bf16 v[128:143], v[112:115], v[148:151], v[80:95]
	ds_read_b128 v[112:115], v221
	s_waitcnt lgkmcnt(0)
	v_mfma_f32_32x32x16_bf16 v[128:143], v[112:115], v[156:159], v[128:143]
	s_nop 5
	v_max3_f32 v112, v96, v97, v98
	v_max_f32_e32 v112, v112, v99
	v_max3_f32 v112, v112, v100, v101
	v_max3_f32 v112, v112, v102, v103
	v_max3_f32 v112, v112, v104, v105
	v_max3_f32 v112, v112, v106, v107
	v_max3_f32 v112, v112, v108, v109
	v_max3_f32 v112, v112, v110, v111
	s_cbranch_vccnz .LBB0_583
	v_cmp_ge_f32_e32 vcc, s85, v112
	s_cmp_lg_u64 vcc, exec
	s_cselect_b64 s[2:3], -1, 0
.LBB0_583:
	s_andn2_b64 vcc, exec, s[2:3]
	s_andn2_b64 s[2:3], exec, s[0:1]
	s_cbranch_vccnz .LBB0_587
	v_and_b32_e32 v65, 64, v196
	v_xor_b32_e32 v64, 32, v196
	v_add_u32_e32 v65, 64, v65
	v_cmp_lt_i32_e32 vcc, v64, v65
	v_max_f32_e32 v65, v112, v112
	s_nop 0
	v_cndmask_b32_e32 v64, v196, v64, vcc
	v_lshlrev_b32_e32 v64, 2, v64
	ds_bpermute_b32 v64, v64, v112
	s_and_b64 vcc, exec, s[2:3]
	s_waitcnt lgkmcnt(0)
	v_max_f32_e32 v64, v64, v64
	v_max_f32_e32 v64, v65, v64
	v_max_f32_e32 v65, 0, v64
	s_cbranch_vccnz .LBB0_586
	v_exp_f32_e64 v66, -v65
	s_nop 0
	v_mul_f32_e32 v220, v220, v66
	v_pk_mul_f32 v[14:15], v[14:15], v[66:67] op_sel_hi:[1,0]
	v_pk_mul_f32 v[12:13], v[12:13], v[66:67] op_sel_hi:[1,0]
	v_pk_mul_f32 v[10:11], v[10:11], v[66:67] op_sel_hi:[1,0]
	v_pk_mul_f32 v[8:9], v[8:9], v[66:67] op_sel_hi:[1,0]
	v_pk_mul_f32 v[6:7], v[6:7], v[66:67] op_sel_hi:[1,0]
	v_pk_mul_f32 v[4:5], v[4:5], v[66:67] op_sel_hi:[1,0]
	v_pk_mul_f32 v[2:3], v[2:3], v[66:67] op_sel_hi:[1,0]
	v_pk_mul_f32 v[0:1], v[0:1], v[66:67] op_sel_hi:[1,0]
	v_pk_mul_f32 v[46:47], v[46:47], v[66:67] op_sel_hi:[1,0]
	v_pk_mul_f32 v[44:45], v[44:45], v[66:67] op_sel_hi:[1,0]
	v_pk_mul_f32 v[42:43], v[42:43], v[66:67] op_sel_hi:[1,0]
	v_pk_mul_f32 v[40:41], v[40:41], v[66:67] op_sel_hi:[1,0]
	v_pk_mul_f32 v[38:39], v[38:39], v[66:67] op_sel_hi:[1,0]
	v_pk_mul_f32 v[36:37], v[36:37], v[66:67] op_sel_hi:[1,0]
	v_pk_mul_f32 v[34:35], v[34:35], v[66:67] op_sel_hi:[1,0]
	v_pk_mul_f32 v[32:33], v[32:33], v[66:67] op_sel_hi:[1,0]

.LBB0_587:
.LBB0_588:
	ds_read_b128 v[162:165], v161 offset:4096
	s_and_b32 s0, s21, 0x100
	s_and_b32 s25, s21, 0x80
	v_bitop3_b32 v166, s25, v179, v207 bitop3:0xde
	s_add_i32 s24, s20, s0
	v_exp_f32_e32 v223, v96
	v_exp_f32_e32 v224, v97
	v_exp_f32_e32 v225, v98
	v_exp_f32_e32 v226, v99
	v_exp_f32_e32 v227, v100
	ds_read_b128 v[96:99], v160 offset:4096
	v_add_u32_e32 v100, s24, v166
	s_waitcnt lgkmcnt(0)
	v_mfma_f32_32x32x16_bf16 v[112:127], v[162:165], v[152:155], v[64:79]
	ds_read_b128 v[168:171], v100 offset:32768
	ds_read_b128 v[160:163], v100 offset:49152
	v_exp_f32_e32 v228, v101
	v_exp_f32_e32 v229, v102
	v_exp_f32_e32 v230, v103
	s_or_b32 s1, s25, 32
	v_bitop3_b32 v167, s1, v179, v207 bitop3:0xde
	v_exp_f32_e32 v231, v104
	v_add_u32_e32 v104, s24, v167
	v_mfma_f32_32x32x16_bf16 v[112:127], v[96:99], v[144:147], v[112:127]
	v_cvt_pk_bf16_f32 v96, v223, v224
	v_cvt_pk_bf16_f32 v97, v225, v226
	v_cvt_pk_bf16_f32 v98, v227, v228
	v_cvt_pk_bf16_f32 v99, v229, v230
	ds_read_b128 v[172:175], v104 offset:32768
	ds_read_b128 v[164:167], v104 offset:49152
	v_exp_f32_e32 v232, v105
	s_waitcnt lgkmcnt(0)
	v_mfma_f32_32x32x16_bf16 v[32:47], v[168:171], v[96:99], v[32:47]
	v_exp_f32_e32 v233, v106
	v_exp_f32_e32 v234, v107
	v_exp_f32_e32 v235, v108
	v_exp_f32_e32 v236, v109
	v_exp_f32_e32 v237, v110
	v_exp_f32_e32 v238, v111
	v_cvt_pk_bf16_f32 v100, v231, v232
	v_mfma_f32_32x32x16_bf16 v[0:15], v[160:163], v[96:99], v[0:15]
	v_cvt_pk_bf16_f32 v101, v233, v234
	v_cvt_pk_bf16_f32 v102, v235, v236
	v_cvt_pk_bf16_f32 v103, v237, v238
	v_max3_f32 v96, v128, v129, v130
	v_max_f32_e32 v96, v96, v131
	v_mfma_f32_32x32x16_bf16 v[32:47], v[172:175], v[100:103], v[32:47]
	v_max3_f32 v96, v96, v132, v133
	v_max3_f32 v96, v96, v134, v135
	v_max3_f32 v96, v96, v136, v137
	v_max3_f32 v96, v96, v138, v139
	v_max3_f32 v96, v96, v140, v141
	v_max3_f32 v96, v96, v142, v143
	s_and_b64 vcc, exec, s[2:3]
	v_mfma_f32_32x32x16_bf16 v[0:15], v[164:167], v[100:103], v[0:15]
	s_mov_b64 s[0:1], s[14:15]
	s_cbranch_vccnz .LBB0_590
	v_cmp_ge_f32_e32 vcc, s85, v96
	s_cmp_lg_u64 vcc, exec
	s_cselect_b64 s[0:1], -1, 0

.LBB0_594:
.LBB0_595:
	v_pk_add_f32 v[192:193], v[224:225], v[226:227]
	v_pk_add_f32 v[194:195], v[228:229], v[230:231]
	v_pk_add_f32 v[198:199], v[232:233], v[234:235]
	v_add_f32_e32 v200, v223, v238
	v_exp_f32_e32 v128, v128
	v_exp_f32_e32 v129, v129
	v_exp_f32_e32 v130, v130
	v_exp_f32_e32 v131, v131
	v_pk_add_f32 v[192:193], v[192:193], v[194:195]
	v_pk_add_f32 v[198:199], v[198:199], v[236:237]
	v_exp_f32_e32 v132, v132
	v_exp_f32_e32 v133, v133
	v_exp_f32_e32 v134, v134
	v_exp_f32_e32 v135, v135
	v_pk_add_f32 v[192:193], v[192:193], v[198:199]
	v_add_f32_e32 v200, v200, v192
	v_add_f32_e32 v200, v200, v193
	v_add_f32_e32 v220, v220, v200
	v_cvt_pk_bf16_f32 v192, v128, v129
	v_cvt_pk_bf16_f32 v193, v130, v131
	v_cvt_pk_bf16_f32 v194, v132, v133
	v_cvt_pk_bf16_f32 v195, v134, v135
	v_exp_f32_e32 v136, v136
	v_exp_f32_e32 v137, v137
	v_mfma_f32_32x32x16_bf16 v[48:63], v[168:171], v[192:195], v[48:63]
	ds_read_b128 v[168:171], v222 offset:4096
	v_exp_f32_e32 v138, v138
	v_exp_f32_e32 v139, v139
	v_exp_f32_e32 v140, v140
	v_exp_f32_e32 v141, v141
	v_exp_f32_e32 v142, v142
	v_exp_f32_e32 v143, v143
	s_waitcnt lgkmcnt(0)
	v_mfma_f32_32x32x16_bf16 v[96:111], v[168:171], v[148:151], v[80:95]
	ds_read_b128 v[168:171], v221 offset:4096
	v_cvt_pk_bf16_f32 v198, v136, v137
	v_cvt_pk_bf16_f32 v199, v138, v139
	v_cvt_pk_bf16_f32 v200, v140, v141
	v_cvt_pk_bf16_f32 v201, v142, v143
	v_mfma_f32_32x32x16_bf16 v[16:31], v[160:163], v[192:195], v[16:31]
	s_waitcnt lgkmcnt(0)
	v_mfma_f32_32x32x16_bf16 v[96:111], v[168:171], v[156:159], v[96:111]
	v_max3_f32 v168, v112, v113, v114
	v_max_f32_e32 v168, v168, v115
	v_max3_f32 v168, v168, v116, v117
	v_max3_f32 v168, v168, v118, v119
	v_max3_f32 v168, v168, v120, v121
	v_mfma_f32_32x32x16_bf16 v[48:63], v[172:175], v[198:201], v[48:63]
	v_max3_f32 v168, v168, v122, v123
	v_max3_f32 v168, v168, v124, v125
	v_max3_f32 v168, v168, v126, v127
	v_cmp_ge_f32_e32 vcc, s85, v168
	s_cmp_eq_u64 vcc, exec
	v_mfma_f32_32x32x16_bf16 v[16:31], v[164:167], v[198:201], v[16:31]
	s_cbranch_scc1 .LBB0_597
	v_and_b32_e32 v65, 64, v196
	v_xor_b32_e32 v64, 32, v196
	v_add_u32_e32 v65, 64, v65
	v_cmp_lt_i32_e32 vcc, v64, v65
	s_nop 1
	v_cndmask_b32_e32 v64, v196, v64, vcc
	v_lshlrev_b32_e32 v64, 2, v64
	ds_bpermute_b32 v64, v64, v168
	s_waitcnt lgkmcnt(0)
	v_max3_f32 v66, v168, v64, 0
	v_exp_f32_e64 v68, -v66
	v_add_f32_e32 v213, v213, v66
	v_xor_b32_e32 v64, 0x80000000, v213
	v_pk_add_f32 v[112:113], v[112:113], v[66:67] op_sel_hi:[1,0] neg_lo:[0,1] neg_hi:[0,1]
	v_pk_mul_f32 v[46:47], v[46:47], v[68:69] op_sel_hi:[1,0]
	v_pk_mul_f32 v[44:45], v[44:45], v[68:69] op_sel_hi:[1,0]
	v_pk_mul_f32 v[42:43], v[42:43], v[68:69] op_sel_hi:[1,0]
	v_pk_mul_f32 v[40:41], v[40:41], v[68:69] op_sel_hi:[1,0]
	v_pk_mul_f32 v[38:39], v[38:39], v[68:69] op_sel_hi:[1,0]
	v_pk_mul_f32 v[36:37], v[36:37], v[68:69] op_sel_hi:[1,0]
	v_pk_mul_f32 v[34:35], v[34:35], v[68:69] op_sel_hi:[1,0]
	v_pk_mul_f32 v[32:33], v[32:33], v[68:69] op_sel_hi:[1,0]
	v_pk_add_f32 v[114:115], v[114:115], v[66:67] op_sel_hi:[1,0] neg_lo:[0,1] neg_hi:[0,1]
	v_pk_add_f32 v[116:117], v[116:117], v[66:67] op_sel_hi:[1,0] neg_lo:[0,1] neg_hi:[0,1]
	v_pk_add_f32 v[118:119], v[118:119], v[66:67] op_sel_hi:[1,0] neg_lo:[0,1] neg_hi:[0,1]
	v_pk_add_f32 v[120:121], v[120:121], v[66:67] op_sel_hi:[1,0] neg_lo:[0,1] neg_hi:[0,1]
	v_pk_add_f32 v[122:123], v[122:123], v[66:67] op_sel_hi:[1,0] neg_lo:[0,1] neg_hi:[0,1]
	v_pk_add_f32 v[124:125], v[124:125], v[66:67] op_sel_hi:[1,0] neg_lo:[0,1] neg_hi:[0,1]
	v_pk_add_f32 v[126:127], v[126:127], v[66:67] op_sel_hi:[1,0] neg_lo:[0,1] neg_hi:[0,1]
	v_mul_f32_e32 v220, v220, v68
	v_pk_mul_f32 v[14:15], v[14:15], v[68:69] op_sel_hi:[1,0]
	v_pk_mul_f32 v[12:13], v[12:13], v[68:69] op_sel_hi:[1,0]
	v_pk_mul_f32 v[10:11], v[10:11], v[68:69] op_sel_hi:[1,0]
	v_pk_mul_f32 v[8:9], v[8:9], v[68:69] op_sel_hi:[1,0]
	v_pk_mul_f32 v[6:7], v[6:7], v[68:69] op_sel_hi:[1,0]
	v_pk_mul_f32 v[4:5], v[4:5], v[68:69] op_sel_hi:[1,0]
	v_pk_mul_f32 v[2:3], v[2:3], v[68:69] op_sel_hi:[1,0]
	v_pk_mul_f32 v[0:1], v[0:1], v[68:69] op_sel_hi:[1,0]
	v_mov_b32_e32 v65, v64
	v_mov_b32_e32 v66, v64
	v_mov_b32_e32 v67, v64
	v_mov_b32_e32 v68, v64
	v_mov_b32_e32 v69, v64
	v_mov_b32_e32 v70, v64
	v_mov_b32_e32 v71, v64
	v_mov_b32_e32 v72, v64
	v_mov_b32_e32 v73, v64
	v_mov_b32_e32 v74, v64
	v_mov_b32_e32 v75, v64
	v_mov_b32_e32 v76, v64
	v_mov_b32_e32 v77, v64
	v_mov_b32_e32 v78, v64
	v_mov_b32_e32 v79, v64
.LBB0_597:
	v_pk_add_f32 v[128:129], v[128:129], v[130:131]
	v_pk_add_f32 v[132:133], v[132:133], v[134:135]
	v_pk_add_f32 v[136:137], v[136:137], v[138:139]
	v_pk_add_f32 v[140:141], v[140:141], v[142:143]
	v_pk_add_f32 v[128:129], v[128:129], v[132:133]
	v_pk_add_f32 v[136:137], v[136:137], v[140:141]
	v_pk_add_f32 v[128:129], v[128:129], v[136:137]
	s_nop 0
	v_add_f32_e32 v128, v128, v129
	v_add_f32_e32 v128, v219, v128
	s_or_b32 s0, s25, 64
	v_bitop3_b32 v161, s0, v179, v207 bitop3:0xde
	v_exp_f32_e32 v133, v116
	v_add_u32_e32 v116, s24, v161
	v_exp_f32_e32 v129, v112
	v_exp_f32_e32 v130, v113
	v_exp_f32_e32 v131, v114
	v_exp_f32_e32 v132, v115
	v_exp_f32_e32 v134, v117
	v_exp_f32_e32 v135, v118
	v_exp_f32_e32 v136, v119
	ds_read_b128 v[112:115], v116 offset:32768
	ds_read_b128 v[116:119], v116 offset:49152
	s_or_b32 s0, s25, 0x60
	v_bitop3_b32 v166, s0, v179, v207 bitop3:0xde
	v_exp_f32_e32 v137, v120
	v_exp_f32_e32 v138, v121
	v_exp_f32_e32 v139, v122
	v_exp_f32_e32 v140, v123
	v_exp_f32_e32 v141, v124
	v_cvt_pk_bf16_f32 v120, v129, v130
	v_cvt_pk_bf16_f32 v121, v131, v132
	v_cvt_pk_bf16_f32 v122, v133, v134
	v_cvt_pk_bf16_f32 v123, v135, v136
	v_add_u32_e32 v124, s24, v166
	v_exp_f32_e32 v142, v125
	v_exp_f32_e32 v143, v126
	v_exp_f32_e32 v160, v127
	s_waitcnt lgkmcnt(0)
	v_mfma_f32_32x32x16_bf16 v[32:47], v[112:115], v[120:123], v[32:47]
	v_cvt_pk_bf16_f32 v162, v137, v138
	v_cvt_pk_bf16_f32 v163, v139, v140
	v_cvt_pk_bf16_f32 v164, v141, v142
	v_cvt_pk_bf16_f32 v165, v143, v160
	v_max3_f32 v161, v96, v97, v98
	v_mfma_f32_32x32x16_bf16 v[0:15], v[116:119], v[120:123], v[0:15]
	ds_read_b128 v[120:123], v124 offset:32768
	ds_read_b128 v[124:127], v124 offset:49152
	s_waitcnt lgkmcnt(0)
	v_mfma_f32_32x32x16_bf16 v[32:47], v[120:123], v[162:165], v[32:47]
	v_mfma_f32_32x32x16_bf16 v[0:15], v[124:127], v[162:165], v[0:15]
	v_max_f32_e32 v161, v161, v99
	v_max3_f32 v161, v161, v100, v101
	v_max3_f32 v161, v161, v102, v103
	v_max3_f32 v161, v161, v104, v105
	v_max3_f32 v161, v161, v106, v107
	v_max3_f32 v161, v161, v108, v109
	v_max3_f32 v161, v161, v110, v111
	v_cmp_ge_f32_e32 vcc, s85, v161
	s_cmp_eq_u64 vcc, exec
	s_cbranch_scc1 .LBB0_580
	v_and_b32_e32 v81, 64, v196
	v_xor_b32_e32 v80, 32, v196
	v_add_u32_e32 v81, 64, v81
	v_cmp_lt_i32_e32 vcc, v80, v81
	s_nop 1
	v_cndmask_b32_e32 v80, v196, v80, vcc
	v_lshlrev_b32_e32 v80, 2, v80
	ds_bpermute_b32 v80, v80, v161
	s_waitcnt lgkmcnt(0)
	v_max3_f32 v82, v161, v80, 0
	v_exp_f32_e64 v84, -v82
	v_add_f32_e32 v214, v214, v82
	v_xor_b32_e32 v80, 0x80000000, v214
	v_pk_add_f32 v[96:97], v[96:97], v[82:83] op_sel_hi:[1,0] neg_lo:[0,1] neg_hi:[0,1]
	v_pk_mul_f32 v[62:63], v[62:63], v[84:85] op_sel_hi:[1,0]
	v_pk_mul_f32 v[60:61], v[60:61], v[84:85] op_sel_hi:[1,0]
	v_pk_mul_f32 v[58:59], v[58:59], v[84:85] op_sel_hi:[1,0]
	v_pk_mul_f32 v[56:57], v[56:57], v[84:85] op_sel_hi:[1,0]
	v_pk_mul_f32 v[54:55], v[54:55], v[84:85] op_sel_hi:[1,0]
	v_pk_mul_f32 v[52:53], v[52:53], v[84:85] op_sel_hi:[1,0]
	v_pk_mul_f32 v[50:51], v[50:51], v[84:85] op_sel_hi:[1,0]
	v_pk_mul_f32 v[48:49], v[48:49], v[84:85] op_sel_hi:[1,0]
	v_pk_add_f32 v[98:99], v[98:99], v[82:83] op_sel_hi:[1,0] neg_lo:[0,1] neg_hi:[0,1]
	v_pk_add_f32 v[100:101], v[100:101], v[82:83] op_sel_hi:[1,0] neg_lo:[0,1] neg_hi:[0,1]
	v_pk_add_f32 v[102:103], v[102:103], v[82:83] op_sel_hi:[1,0] neg_lo:[0,1] neg_hi:[0,1]
	v_pk_add_f32 v[104:105], v[104:105], v[82:83] op_sel_hi:[1,0] neg_lo:[0,1] neg_hi:[0,1]
	v_pk_add_f32 v[106:107], v[106:107], v[82:83] op_sel_hi:[1,0] neg_lo:[0,1] neg_hi:[0,1]
	v_pk_add_f32 v[108:109], v[108:109], v[82:83] op_sel_hi:[1,0] neg_lo:[0,1] neg_hi:[0,1]
	v_pk_add_f32 v[110:111], v[110:111], v[82:83] op_sel_hi:[1,0] neg_lo:[0,1] neg_hi:[0,1]
	v_mul_f32_e32 v128, v128, v84
	v_pk_mul_f32 v[30:31], v[30:31], v[84:85] op_sel_hi:[1,0]
	v_pk_mul_f32 v[28:29], v[28:29], v[84:85] op_sel_hi:[1,0]
	v_pk_mul_f32 v[26:27], v[26:27], v[84:85] op_sel_hi:[1,0]
	v_pk_mul_f32 v[24:25], v[24:25], v[84:85] op_sel_hi:[1,0]
	v_pk_mul_f32 v[22:23], v[22:23], v[84:85] op_sel_hi:[1,0]
	v_pk_mul_f32 v[20:21], v[20:21], v[84:85] op_sel_hi:[1,0]
	v_pk_mul_f32 v[18:19], v[18:19], v[84:85] op_sel_hi:[1,0]
	v_pk_mul_f32 v[16:17], v[16:17], v[84:85] op_sel_hi:[1,0]
	v_mov_b32_e32 v81, v80
	v_mov_b32_e32 v82, v80
	v_mov_b32_e32 v83, v80
	v_mov_b32_e32 v84, v80
	v_mov_b32_e32 v85, v80
	v_mov_b32_e32 v86, v80
	v_mov_b32_e32 v87, v80
	v_mov_b32_e32 v88, v80
	v_mov_b32_e32 v89, v80
	v_mov_b32_e32 v90, v80
	v_mov_b32_e32 v91, v80
	v_mov_b32_e32 v92, v80
	v_mov_b32_e32 v93, v80
	v_mov_b32_e32 v94, v80
	v_mov_b32_e32 v95, v80
	s_branch .LBB0_580
